# page items in P1 tail on WG>=180
# speedup vs baseline: 1.0037x; 1.0037x over previous
.LBB0_7:
	s_nop 0
	v_readlane_b32 s0, v254, 2
	v_readlane_b32 s1, v254, 3
	v_writelane_b32 v254, s48, 40
	s_cmp_lt_i32 s0, 1
	s_cselect_b64 s[4:5], -1, 0
	v_writelane_b32 v254, s49, 41
	v_writelane_b32 v254, s50, 42
	s_cmp_gt_i32 s1, 0
	v_writelane_b32 v254, s51, 43
	s_cselect_b64 s[6:7], -1, 0
	v_writelane_b32 v254, s52, 44
	s_and_b64 s[6:7], s[4:5], s[6:7]
	v_writelane_b32 v254, s53, 45
	s_andn2_b64 vcc, exec, s[6:7]
	v_and_b32_e32 v206, 63, v0
	v_writelane_b32 v254, s54, 46
	v_writelane_b32 v254, s55, 47
	s_cbranch_vccnz .LBB0_113
	s_movk_i32 s98, 0x2a7f
	v_readlane_b32 s0, v254, 0
	v_readlane_b32 s1, v254, 1
	s_load_dword s8, s[0:1], 0xe8
	v_readfirstlane_b32 s0, v0
	s_lshr_b32 s9, s0, 6
	s_lshl_b32 s0, s2, 3
	s_add_i32 s10, s9, s0
	s_waitcnt lgkmcnt(0)
	s_cmp_le_u32 s8, 180
	s_cbranch_scc1 .Lrc_nb
	s_sub_u32 s0, s8, 180
	s_lshl_b32 s0, s0, 3
	s_sub_u32 s98, s98, s0

.LBB0_325:
	s_cmp_eq_u32 s99, 5
	s_cbranch_scc0 .Lrc_p1skip
	s_cmp_lt_u32 s100, 180
	s_cbranch_scc1 .Lrc_p1skip
	s_mov_b32 s99, 7
	s_mov_b64 exec, -1
	v_readlane_b32 s0, v254, 0
	v_readlane_b32 s1, v254, 1
	v_readlane_b32 s52, v254, 44
	v_readlane_b32 s53, v254, 45
	v_readlane_b32 s54, v254, 46
	v_readlane_b32 s55, v254, 47
	s_nop 4
	s_load_dwordx16 s[76:91], s[0:1], 0x0
	s_load_dword s8, s[0:1], 0xe8
	s_waitcnt lgkmcnt(0)
	s_add_u32 s2, s100, 0x550
	s_sub_u32 s2, s2, s8
	s_sub_u32 s8, s8, 180
	s_movk_i32 s98, 0x2a7f
	v_readfirstlane_b32 s9, v0
	s_lshr_b32 s9, s9, 6
	s_lshl_b32 s10, s2, 3
	s_add_u32 s10, s10, s9
	s_lshl_b32 s3, s8, 3
	v_and_b32_e32 v34, 63, v0
	s_branch .LBB0_78
